# after a SwiGLU epilogue the next tile's K-loop is entered with vmcnt(8) (the wave's 8 ACT stores may still be in flight) instead of vmcnt(0)
# baseline (speedup 1.0000x reference)
; #define PG8_STAGE(bufoff, gbase, voff) do { _Pragma("unroll") for (int _i = 0; _i < 2; ++_i) \
;         __builtin_amdgcn_global_load_lds((const unsigned*)((const char*)(gbase) + (voff)[_i]), (PG8_LAS unsigned*)(lds + (bufoff) + ldsw + _i * 8192), 16, 0, 0); } while (0)
; #define PG8_WAIT_V(n) asm volatile("s_waitcnt vmcnt(" #n ")" ::: "memory")
; #define PG8_BAR __builtin_amdgcn_s_barrier()
; template <class Epi, class Sched, bool ALIGN_EPI = false, bool SP2 = false>
; __device__ __forceinline__ void gemm_phase(PG8_LAS unsigned char* lds, const Gemm g, const Sched& S, const Epi& E) {
;     int tid = (int)threadIdx.x; asm volatile("" : "+v"(tid)); const int wid = __builtin_amdgcn_readfirstlane(tid >> 6), lane = tid & 63, wr = wid >> 2, wc = wid & 3, fr = lane & 15, fq = lane >> 4;
;     const int K = g.K, nt = K / BK;
;     unsigned voffA[2], voffB[2];
; #pragma unroll
;     for (int i = 0; i < 2; ++i) { int R, C; stage_rc(tid * 16 + i * 8192, R, C); const int Rb = Epi::PERM ? ((R & ~31) + perm32(R & 31)) : R;
;         voffA[i] = (unsigned)(R * K + C) * 2u; voffB[i] = (unsigned)(Rb * K + C) * 2u; }
;     const size_t kstep = (size_t)(BK * 2);
;     const size_t hstep = (size_t)HALF * K * 2;
;     const size_t tstep = 2 * hstep;
;     const unsigned ldsw = (unsigned)wid * 1024u;
;     const int aoff = lds_byte(wr * 64 + fr, fq * 8), boff = lds_byte(wc * 32 + fr, fq * 8);
;     ...
;         PG8_STAGE(PG8_SB(1, 0), cB + kstep, voffB); PG8_STAGE(PG8_SA(1, 0), cA + kstep, voffA); PG8_STAGE(PG8_SB(1, 1), cB + hstep + kstep, voffB);
;         PG8_WAIT_V(6); PG8_BAR;
.LBB0_49:
	s_add_i32 m0, s58, 0x18000
	v_lshl_add_u64 v[10:11], v[10:11], 0, s[2:3]
	s_waitcnt vmcnt(2)
	s_barrier
	global_load_lds_dwordx4 v[10:11], off
	v_lshl_add_u64 v[6:7], v[6:7], 0, s[2:3]
	s_add_i32 m0, s58, 0x1a000
	s_add_i32 s62, s58, 0x8000
	global_load_lds_dwordx4 v[6:7], off
	v_lshl_add_u64 v[6:7], v[8:9], 0, s[2:3]
	s_mov_b32 m0, s62
	s_add_i32 s63, s58, 0xa000
	global_load_lds_dwordx4 v[6:7], off
	v_lshl_add_u64 v[6:7], v[12:13], 0, s[2:3]
	s_mov_b32 m0, s63
	v_lshl_add_u64 v[4:5], v[4:5], 0, s[2:3]
	global_load_lds_dwordx4 v[6:7], off
	s_add_i32 m0, s58, 0x1c000
	v_lshl_add_u64 v[2:3], v[2:3], 0, s[2:3]
	global_load_lds_dwordx4 v[4:5], off
	s_add_i32 m0, s58, 0x1e000
	v_and_b32_e32 v4, 15, v14
	global_load_lds_dwordx4 v[2:3], off
	v_bfe_u32 v3, v14, 4, 2
	v_lshlrev_b32_e32 v5, 4, v3
	v_lshl_or_b32 v1, s5, 6, v4
	v_lshl_or_b32 v4, v4, 6, v5
	v_lshlrev_b32_e32 v5, 2, v14
	s_and_b32 s64, s4, 3
	s_lshr_b32 s65, s20, 6
	s_lshl_b32 s5, s5, 13
	v_and_b32_e32 v5, 32, v5
	v_bitop3_b32 v6, v4, s5, v5 bitop3:0xde
	s_lshl_b32 s66, s64, 5
	s_lshl_b32 s5, s64, 12
	s_add_i32 s67, s65, -2
	s_cmpk_lt_u32 s24, 0x100
	s_cselect_b64 s[24:25], -1, 0
	s_lshl_b32 s71, s15, 3
	v_bitop3_b32 v227, v4, s5, v5 bitop3:0xde
	v_cvt_f32_ubyte0_e32 v4, s71
	v_rcp_iflag_f32_e32 v4, v4
	v_lshrrev_b32_e32 v2, 4, v14
	v_bitop3_b32 v2, s4, v2, 3 bitop3:0xa8
	v_cmp_eq_u32_e64 s[40:41], 0, v2
	v_mul_f32_e32 v2, 0x4f7ffffe, v4
	v_cvt_u32_f32_e32 v2, v2
	v_readlane_b32 s4, v237, 58
	v_readlane_b32 s5, v237, 59
	s_mov_b32 s15, s5
	v_readfirstlane_b32 s5, v2
	v_add_u32_e32 v2, v17, v15
	v_lshlrev_b32_e32 v178, 3, v3
	v_cmp_eq_u32_e64 s[42:43], 0, v3
	s_sub_i32 s4, 0, s71
	v_add_lshl_u32 v2, v2, v16, 1
	v_mov_b32_e32 v3, v0
	s_waitcnt vmcnt(6)
	s_mul_i32 s4, s4, s5
	v_lshl_add_u64 v[180:181], s[16:17], 0, v[2:3]
	v_add_u32_e32 v2, v20, v18
	s_lshl_b32 s68, s64, 6
	s_mul_hi_u32 s4, s5, s4
	v_add_lshl_u32 v2, v2, v19, 1
	v_or_b32_e32 v228, s66, v178
	s_or_b32 s69, s68, 32
	s_or_b32 s70, s66, 0x80
	s_mov_b32 s72, 0
	s_add_i32 s73, s5, s4
	v_lshl_add_u64 v[182:183], s[16:17], 0, v[2:3]
	v_add_u32_e32 v229, 0, v6
	s_mov_b32 s90, 0
	s_barrier
	s_branch .LBB0_52

; template <class Epi, class Sched, bool ALIGN_EPI = false, bool SP2 = false>
; __device__ __forceinline__ void gemm_phase(PG8_LAS unsigned char* lds, const Gemm g, const Sched& S, const Epi& E) {
;     ...
; #pragma unroll
;         for (int a = 0; a < 2; ++a)
; #pragma unroll
;             for (int b = 0; b < 2; ++b)
; #pragma unroll
;                 for (int m = 0; m < 4; ++m)
; #pragma unroll
;                     for (int n = 0; n < 2; ++n) acc[a][b][m][n] = (f32x4){0.f, 0.f, 0.f, 0.f};
;         cur = nxt; cA = nA; cB = nB; ++ui;
.LBB0_58:
	s_add_u32 s4, s38, 0x80
	s_addc_u32 s5, s39, 0
	s_add_u32 s20, s34, 0x100
	s_addc_u32 s38, s35, 0
	s_mov_b32 s34, 0
	v_mov_b64_e32 v[2:3], 0
	v_mov_b64_e32 v[4:5], 0
	v_mov_b64_e32 v[6:7], 0
	v_mov_b64_e32 v[8:9], 0
	v_mov_b64_e32 v[10:11], 0
	v_mov_b64_e32 v[12:13], 0
	v_mov_b64_e32 v[14:15], 0
	v_mov_b64_e32 v[16:17], 0
	v_mov_b64_e32 v[18:19], 0
	v_mov_b64_e32 v[20:21], 0
	v_mov_b64_e32 v[22:23], 0
	v_mov_b64_e32 v[24:25], 0
	v_mov_b64_e32 v[26:27], 0
	v_mov_b64_e32 v[28:29], 0
	v_mov_b64_e32 v[30:31], 0
	v_mov_b64_e32 v[32:33], 0
	v_mov_b64_e32 v[34:35], 0
	v_mov_b64_e32 v[36:37], 0
	v_mov_b64_e32 v[38:39], 0
	v_mov_b64_e32 v[40:41], 0
	v_mov_b64_e32 v[42:43], 0
	v_mov_b64_e32 v[44:45], 0
	v_mov_b64_e32 v[46:47], 0
	v_mov_b64_e32 v[48:49], 0
	v_mov_b64_e32 v[50:51], 0
	v_mov_b64_e32 v[52:53], 0
	v_mov_b64_e32 v[54:55], 0
	v_mov_b64_e32 v[56:57], 0
	v_mov_b64_e32 v[58:59], 0
	v_mov_b64_e32 v[60:61], 0
	v_mov_b64_e32 v[62:63], 0
	v_mov_b64_e32 v[64:65], 0
	v_mov_b64_e32 v[66:67], 0
	v_mov_b64_e32 v[68:69], 0
	v_mov_b64_e32 v[70:71], 0
	v_mov_b64_e32 v[72:73], 0
	v_mov_b64_e32 v[74:75], 0
	v_mov_b64_e32 v[76:77], 0
	v_mov_b64_e32 v[78:79], 0
	v_mov_b64_e32 v[80:81], 0
	v_mov_b64_e32 v[82:83], 0
	v_mov_b64_e32 v[84:85], 0
	v_mov_b64_e32 v[86:87], 0
	v_mov_b64_e32 v[88:89], 0
	v_mov_b64_e32 v[90:91], 0
	v_mov_b64_e32 v[92:93], 0
	v_mov_b64_e32 v[94:95], 0
	v_mov_b64_e32 v[96:97], 0
	v_mov_b64_e32 v[98:99], 0
	v_mov_b64_e32 v[100:101], 0
	v_mov_b64_e32 v[102:103], 0
	v_mov_b64_e32 v[104:105], 0
	v_mov_b64_e32 v[106:107], 0
	v_mov_b64_e32 v[108:109], 0
	s_cmp_eq_u32 s90, 1
	s_mov_b32 s90, 0
	s_cbranch_scc1 .Lmy_z8
	s_waitcnt vmcnt(0)
	s_branch .Lmy_zj
.Lmy_z8:
	s_waitcnt vmcnt(8)
.Lmy_zj:
	v_mov_b64_e32 v[110:111], 0
	v_mov_b64_e32 v[112:113], 0
	v_mov_b64_e32 v[114:115], 0
	v_mov_b64_e32 v[116:117], 0
	v_mov_b64_e32 v[118:119], 0
	v_mov_b64_e32 v[120:121], 0
	v_mov_b64_e32 v[122:123], 0
	v_mov_b64_e32 v[124:125], 0
	v_mov_b64_e32 v[126:127], 0
	v_mov_b64_e32 v[128:129], 0

; #define PG8_BAR __builtin_amdgcn_s_barrier()
; template <class Epi, class Sched, bool ALIGN_EPI = false, bool SP2 = false>
; __device__ __forceinline__ void gemm_phase(PG8_LAS unsigned char* lds, const Gemm g, const Sched& S, const Epi& E) {
;     ...
;         if constexpr (ALIGN_EPI) { if (wr == 0) PG8_BAR; }
;         if constexpr (!Epi::AFTER_DRAIN) { E(acc, cur, wr, wc, fr, fq); S.done(cur); }
; __device__ __forceinline__ void epi_all_run(const void* Pk_, int l, int s, const f32x4 (&acc)[2][2][4][2], const pg8::Unit& u, int wr, int wc, int fr, int fq) {
;         CA* Pl = (CA*)Pk_; asm volatile("" : "+s"(Pl), "+s"(l), "+s"(s)); CA& A = *Pl;
;         unsigned char* const ws = A.ws;
;         const int row0 = u.pm * 256 + wr * 64 + fr; const int b = u.pm >> 4;
;         if (s == 0 || s == 5) {
.LBB0_62:
	v_readlane_b32 s4, v238, 2
	v_readlane_b32 s5, v238, 3
	s_mov_b32 s90, 0
	s_mov_b32 s76, s37
	s_mov_b32 s75, s88
	s_load_dwordx2 s[34:35], s[4:5], 0xc8
	s_cmp_lt_i32 s76, 2
	v_lshl_add_u32 v184, s31, 8, v1
	s_cbranch_scc1 .LBB0_65
	s_cmp_gt_i32 s76, 4
	s_cbranch_scc0 .LBB0_66
	s_cmp_lg_u32 s76, 5
	s_mov_b64 s[38:39], -1
	s_cselect_b64 s[46:47], -1, 0
	s_cbranch_execz .LBB0_67
	s_branch .LBB0_88

; __device__ __forceinline__ unsigned pk2(float lo, float hi) { f32x2_t v = {lo, hi}; bf16x2_t b = __builtin_convertvector(v, bf16x2_t); return __builtin_bit_cast(unsigned, b); }
; __device__ __forceinline__ float fast_sigmoid(float x) { return __builtin_amdgcn_rcpf(1.0f + __builtin_amdgcn_exp2f(-x * LOG2E)); }
; __device__ __forceinline__ void epi_all_run(const void* Pk_, int l, int s, const f32x4 (&acc)[2][2][4][2], const pg8::Unit& u, int wr, int wc, int fr, int fq) {
;     ...
;         if (s == 0 || s == 5) {
;             bf16_t* O = (bf16_t*)(ws + WS_ACT);
;             const int col0 = u.pn * 128 + wc * 32 + 8 * fq;
; #pragma unroll
;             for (int ai = 0; ai < 2; ++ai)
; #pragma unroll
;                 for (int m = 0; m < 4; ++m) {
;                     bf16_t* rowp = O + (size_t)(row0 + ai * 128 + m * 16) * DFF + col0;
;                     float r[8];
; #pragma unroll
;                     for (int n = 0; n < 2; ++n)
; #pragma unroll
;                         for (int j = 0; j < 4; ++j) { const float g = acc[ai][0][m][n][j], up = acc[ai][1][m][n][j]; r[n * 4 + j] = g * fast_sigmoid(g) * up; }
;                     v4u w; w.x = pk2(r[0], r[1]); w.y = pk2(r[2], r[3]); w.z = pk2(r[4], r[5]); w.w = pk2(r[6], r[7]);
;                     *(v4u*)rowp = w;
;                 }
.LBB0_125:
	s_and_b64 vcc, exec, s[38:39]
	s_cbranch_vccz .LBB0_124
	s_waitcnt lgkmcnt(0)
	v_lshl_or_b32 v130, s30, 7, v228
	s_mov_b32 s6, 0xbfb8aa3b
	v_ashrrev_i32_e32 v131, 31, v130
	s_mov_b64 s[4:5], 0x9500000
	v_lshl_add_u64 v[130:131], v[130:131], 1, s[34:35]
	s_movk_i32 s20, 0x1600
	v_lshl_add_u64 v[130:131], v[130:131], 0, s[4:5]
	v_pk_mul_f32 v[118:119], v[118:119], v[126:127]
	v_pk_mul_f32 v[120:121], v[120:121], v[128:129]
	v_pk_mul_f32 v[114:115], v[114:115], v[122:123]
	v_pk_mul_f32 v[116:117], v[116:117], v[124:125]
	v_pk_mul_f32 v[126:127], v[126:127], s[6:7] op_sel_hi:[1,0]
	v_pk_mul_f32 v[128:129], v[128:129], s[6:7] op_sel_hi:[1,0]
	v_pk_mul_f32 v[122:123], v[122:123], s[6:7] op_sel_hi:[1,0]
	v_pk_mul_f32 v[124:125], v[124:125], s[6:7] op_sel_hi:[1,0]
	v_exp_f32_e32 v126, v126
	v_exp_f32_e32 v127, v127
	v_exp_f32_e32 v128, v128
	v_exp_f32_e32 v129, v129
	v_exp_f32_e32 v122, v122
	v_exp_f32_e32 v123, v123
	v_exp_f32_e32 v124, v124
	v_exp_f32_e32 v125, v125
	v_pk_add_f32 v[126:127], v[126:127], 1.0 op_sel_hi:[1,0]
	v_pk_add_f32 v[128:129], v[128:129], 1.0 op_sel_hi:[1,0]
	v_pk_add_f32 v[122:123], v[122:123], 1.0 op_sel_hi:[1,0]
	v_pk_add_f32 v[124:125], v[124:125], 1.0 op_sel_hi:[1,0]
	v_rcp_f32_e32 v126, v126
	v_rcp_f32_e32 v127, v127
	v_rcp_f32_e32 v128, v128
	v_rcp_f32_e32 v129, v129
	v_rcp_f32_e32 v122, v122
	v_rcp_f32_e32 v123, v123
	v_rcp_f32_e32 v124, v124
	v_rcp_f32_e32 v125, v125
	v_pk_mul_f32 v[118:119], v[118:119], v[126:127]
	v_pk_mul_f32 v[120:121], v[120:121], v[128:129]
	v_pk_mul_f32 v[114:115], v[114:115], v[122:123]
	v_pk_mul_f32 v[116:117], v[116:117], v[124:125]
	v_cvt_pk_bf16_f32 v126, v118, v119
	v_cvt_pk_bf16_f32 v127, v120, v121
	v_cvt_pk_bf16_f32 v128, v114, v115
	v_cvt_pk_bf16_f32 v129, v116, v117
	v_mad_i64_i32 v[132:133], s[8:9], v184, s20, v[130:131]
	global_store_dwordx4 v[132:133], v[126:129], off
	v_pk_mul_f32 v[102:103], v[102:103], v[110:111]
	v_pk_mul_f32 v[104:105], v[104:105], v[112:113]
	v_pk_mul_f32 v[98:99], v[98:99], v[106:107]
	v_pk_mul_f32 v[100:101], v[100:101], v[108:109]
	v_pk_mul_f32 v[110:111], v[110:111], s[6:7] op_sel_hi:[1,0]
	v_pk_mul_f32 v[112:113], v[112:113], s[6:7] op_sel_hi:[1,0]
	v_pk_mul_f32 v[106:107], v[106:107], s[6:7] op_sel_hi:[1,0]
	v_pk_mul_f32 v[108:109], v[108:109], s[6:7] op_sel_hi:[1,0]
	v_exp_f32_e32 v110, v110
	v_exp_f32_e32 v111, v111
	v_exp_f32_e32 v112, v112
	v_exp_f32_e32 v113, v113
	v_exp_f32_e32 v106, v106
	v_exp_f32_e32 v107, v107
	v_exp_f32_e32 v108, v108
	v_exp_f32_e32 v109, v109
	v_pk_add_f32 v[110:111], v[110:111], 1.0 op_sel_hi:[1,0]
	v_pk_add_f32 v[112:113], v[112:113], 1.0 op_sel_hi:[1,0]
	v_pk_add_f32 v[106:107], v[106:107], 1.0 op_sel_hi:[1,0]
	v_pk_add_f32 v[108:109], v[108:109], 1.0 op_sel_hi:[1,0]
	v_rcp_f32_e32 v110, v110
	v_rcp_f32_e32 v111, v111
	v_rcp_f32_e32 v112, v112
	v_rcp_f32_e32 v113, v113
	v_rcp_f32_e32 v106, v106
	v_rcp_f32_e32 v107, v107
	v_rcp_f32_e32 v108, v108
	v_rcp_f32_e32 v109, v109
	v_pk_mul_f32 v[102:103], v[102:103], v[110:111]
	v_pk_mul_f32 v[104:105], v[104:105], v[112:113]
	v_pk_mul_f32 v[98:99], v[98:99], v[106:107]
	v_pk_mul_f32 v[100:101], v[100:101], v[108:109]
	v_cvt_pk_bf16_f32 v110, v102, v103
	v_cvt_pk_bf16_f32 v111, v104, v105
	v_cvt_pk_bf16_f32 v112, v98, v99
	v_cvt_pk_bf16_f32 v113, v100, v101
	v_mad_i64_i32 v[132:133], s[8:9], v186, s20, v[130:131]
	global_store_dwordx4 v[132:133], v[110:113], off
	v_pk_mul_f32 v[86:87], v[86:87], v[94:95]
	v_pk_mul_f32 v[88:89], v[88:89], v[96:97]
	v_pk_mul_f32 v[82:83], v[82:83], v[90:91]
	v_pk_mul_f32 v[84:85], v[84:85], v[92:93]
	v_pk_mul_f32 v[94:95], v[94:95], s[6:7] op_sel_hi:[1,0]
	v_pk_mul_f32 v[96:97], v[96:97], s[6:7] op_sel_hi:[1,0]
	v_pk_mul_f32 v[90:91], v[90:91], s[6:7] op_sel_hi:[1,0]
	v_pk_mul_f32 v[92:93], v[92:93], s[6:7] op_sel_hi:[1,0]
	v_exp_f32_e32 v94, v94
	v_exp_f32_e32 v95, v95
	v_exp_f32_e32 v96, v96
	v_exp_f32_e32 v97, v97
	v_exp_f32_e32 v90, v90
	v_exp_f32_e32 v91, v91
	v_exp_f32_e32 v92, v92
	v_exp_f32_e32 v93, v93
	v_pk_add_f32 v[94:95], v[94:95], 1.0 op_sel_hi:[1,0]
	v_pk_add_f32 v[96:97], v[96:97], 1.0 op_sel_hi:[1,0]
	v_pk_add_f32 v[90:91], v[90:91], 1.0 op_sel_hi:[1,0]
	v_pk_add_f32 v[92:93], v[92:93], 1.0 op_sel_hi:[1,0]
	v_rcp_f32_e32 v94, v94
	v_rcp_f32_e32 v95, v95
	v_rcp_f32_e32 v96, v96
	v_rcp_f32_e32 v97, v97
	v_rcp_f32_e32 v90, v90
	v_rcp_f32_e32 v91, v91
	v_rcp_f32_e32 v92, v92
	v_rcp_f32_e32 v93, v93
	v_pk_mul_f32 v[86:87], v[86:87], v[94:95]
	v_pk_mul_f32 v[88:89], v[88:89], v[96:97]
	v_pk_mul_f32 v[82:83], v[82:83], v[90:91]
	v_pk_mul_f32 v[84:85], v[84:85], v[92:93]
	v_cvt_pk_bf16_f32 v94, v86, v87
	v_cvt_pk_bf16_f32 v95, v88, v89
	v_cvt_pk_bf16_f32 v96, v82, v83
	v_cvt_pk_bf16_f32 v97, v84, v85
	v_or_b32_e32 v86, 32, v184
	v_mad_i64_i32 v[132:133], s[8:9], v86, s20, v[130:131]
	global_store_dwordx4 v[132:133], v[94:97], off
	v_pk_mul_f32 v[70:71], v[70:71], v[78:79]
	v_pk_mul_f32 v[72:73], v[72:73], v[80:81]
	v_pk_mul_f32 v[66:67], v[66:67], v[74:75]
	v_pk_mul_f32 v[68:69], v[68:69], v[76:77]
	v_pk_mul_f32 v[78:79], v[78:79], s[6:7] op_sel_hi:[1,0]
	v_pk_mul_f32 v[80:81], v[80:81], s[6:7] op_sel_hi:[1,0]
	v_pk_mul_f32 v[74:75], v[74:75], s[6:7] op_sel_hi:[1,0]
	v_pk_mul_f32 v[76:77], v[76:77], s[6:7] op_sel_hi:[1,0]
	v_exp_f32_e32 v78, v78
	v_exp_f32_e32 v79, v79
	v_exp_f32_e32 v80, v80
	v_exp_f32_e32 v81, v81
	v_exp_f32_e32 v74, v74
	v_exp_f32_e32 v75, v75
	v_exp_f32_e32 v76, v76
	v_exp_f32_e32 v77, v77
	v_pk_add_f32 v[78:79], v[78:79], 1.0 op_sel_hi:[1,0]
	v_pk_add_f32 v[80:81], v[80:81], 1.0 op_sel_hi:[1,0]
	v_pk_add_f32 v[74:75], v[74:75], 1.0 op_sel_hi:[1,0]
	v_pk_add_f32 v[76:77], v[76:77], 1.0 op_sel_hi:[1,0]
; __device__ __forceinline__ unsigned pk2(float lo, float hi) { f32x2_t v = {lo, hi}; bf16x2_t b = __builtin_convertvector(v, bf16x2_t); return __builtin_bit_cast(unsigned, b); }
; __device__ __forceinline__ float fast_sigmoid(float x) { return __builtin_amdgcn_rcpf(1.0f + __builtin_amdgcn_exp2f(-x * LOG2E)); }
; __device__ __forceinline__ void epi_all_run(const void* Pk_, int l, int s, const f32x4 (&acc)[2][2][4][2], const pg8::Unit& u, int wr, int wc, int fr, int fq) {
;     ...
;         if (s == 0 || s == 5) {
;             bf16_t* O = (bf16_t*)(ws + WS_ACT);
;             const int col0 = u.pn * 128 + wc * 32 + 8 * fq;
; #pragma unroll
;             for (int ai = 0; ai < 2; ++ai)
; #pragma unroll
;                 for (int m = 0; m < 4; ++m) {
;                     bf16_t* rowp = O + (size_t)(row0 + ai * 128 + m * 16) * DFF + col0;
;                     float r[8];
; #pragma unroll
;                     for (int n = 0; n < 2; ++n)
; #pragma unroll
;                         for (int j = 0; j < 4; ++j) { const float g = acc[ai][0][m][n][j], up = acc[ai][1][m][n][j]; r[n * 4 + j] = g * fast_sigmoid(g) * up; }
;                     v4u w; w.x = pk2(r[0], r[1]); w.y = pk2(r[2], r[3]); w.z = pk2(r[4], r[5]); w.w = pk2(r[6], r[7]);
;                     *(v4u*)rowp = w;
;                 }
	v_rcp_f32_e32 v78, v78
	v_rcp_f32_e32 v79, v79
	v_rcp_f32_e32 v80, v80
	v_rcp_f32_e32 v81, v81
	v_rcp_f32_e32 v74, v74
	v_rcp_f32_e32 v75, v75
	v_rcp_f32_e32 v76, v76
	v_rcp_f32_e32 v77, v77
	v_pk_mul_f32 v[70:71], v[70:71], v[78:79]
	v_pk_mul_f32 v[72:73], v[72:73], v[80:81]
	v_pk_mul_f32 v[66:67], v[66:67], v[74:75]
	v_pk_mul_f32 v[68:69], v[68:69], v[76:77]
	v_cvt_pk_bf16_f32 v78, v70, v71
	v_cvt_pk_bf16_f32 v79, v72, v73
	v_cvt_pk_bf16_f32 v80, v66, v67
	v_cvt_pk_bf16_f32 v81, v68, v69
	v_or_b32_e32 v70, 48, v184
	v_mad_i64_i32 v[132:133], s[8:9], v70, s20, v[130:131]
	global_store_dwordx4 v[132:133], v[78:81], off
	v_pk_mul_f32 v[54:55], v[54:55], v[62:63]
	v_pk_mul_f32 v[56:57], v[56:57], v[64:65]
	v_pk_mul_f32 v[50:51], v[50:51], v[58:59]
	v_pk_mul_f32 v[52:53], v[52:53], v[60:61]
	v_pk_mul_f32 v[62:63], v[62:63], s[6:7] op_sel_hi:[1,0]
	v_pk_mul_f32 v[64:65], v[64:65], s[6:7] op_sel_hi:[1,0]
	v_pk_mul_f32 v[58:59], v[58:59], s[6:7] op_sel_hi:[1,0]
	v_pk_mul_f32 v[60:61], v[60:61], s[6:7] op_sel_hi:[1,0]
	v_exp_f32_e32 v62, v62
	v_exp_f32_e32 v63, v63
	v_exp_f32_e32 v64, v64
	v_exp_f32_e32 v65, v65
	v_exp_f32_e32 v58, v58
	v_exp_f32_e32 v59, v59
	v_exp_f32_e32 v60, v60
	v_exp_f32_e32 v61, v61
	v_pk_add_f32 v[62:63], v[62:63], 1.0 op_sel_hi:[1,0]
	v_pk_add_f32 v[64:65], v[64:65], 1.0 op_sel_hi:[1,0]
	v_pk_add_f32 v[58:59], v[58:59], 1.0 op_sel_hi:[1,0]
	v_pk_add_f32 v[60:61], v[60:61], 1.0 op_sel_hi:[1,0]
	v_rcp_f32_e32 v62, v62
	v_rcp_f32_e32 v63, v63
	v_rcp_f32_e32 v64, v64
	v_rcp_f32_e32 v65, v65
	v_rcp_f32_e32 v58, v58
	v_rcp_f32_e32 v59, v59
	v_rcp_f32_e32 v60, v60
	v_rcp_f32_e32 v61, v61
	v_pk_mul_f32 v[54:55], v[54:55], v[62:63]
	v_pk_mul_f32 v[56:57], v[56:57], v[64:65]
	v_pk_mul_f32 v[50:51], v[50:51], v[58:59]
	v_pk_mul_f32 v[52:53], v[52:53], v[60:61]
	v_cvt_pk_bf16_f32 v62, v54, v55
	v_cvt_pk_bf16_f32 v63, v56, v57
	v_cvt_pk_bf16_f32 v64, v50, v51
	v_cvt_pk_bf16_f32 v65, v52, v53
	v_add_u32_e32 v54, 0x80, v184
	v_mad_i64_i32 v[132:133], s[8:9], v54, s20, v[130:131]
	global_store_dwordx4 v[132:133], v[62:65], off
	v_pk_mul_f32 v[38:39], v[38:39], v[46:47]
	v_pk_mul_f32 v[40:41], v[40:41], v[48:49]
	v_pk_mul_f32 v[34:35], v[34:35], v[42:43]
	v_pk_mul_f32 v[36:37], v[36:37], v[44:45]
	v_pk_mul_f32 v[46:47], v[46:47], s[6:7] op_sel_hi:[1,0]
	v_pk_mul_f32 v[48:49], v[48:49], s[6:7] op_sel_hi:[1,0]
	v_pk_mul_f32 v[42:43], v[42:43], s[6:7] op_sel_hi:[1,0]
	v_pk_mul_f32 v[44:45], v[44:45], s[6:7] op_sel_hi:[1,0]
	v_exp_f32_e32 v46, v46
	v_exp_f32_e32 v47, v47
	v_exp_f32_e32 v48, v48
	v_exp_f32_e32 v49, v49
	v_exp_f32_e32 v42, v42
	v_exp_f32_e32 v43, v43
	v_exp_f32_e32 v44, v44
	v_exp_f32_e32 v45, v45
	v_pk_add_f32 v[46:47], v[46:47], 1.0 op_sel_hi:[1,0]
	v_pk_add_f32 v[48:49], v[48:49], 1.0 op_sel_hi:[1,0]
	v_pk_add_f32 v[42:43], v[42:43], 1.0 op_sel_hi:[1,0]
	v_pk_add_f32 v[44:45], v[44:45], 1.0 op_sel_hi:[1,0]
	v_rcp_f32_e32 v46, v46
	v_rcp_f32_e32 v47, v47
	v_rcp_f32_e32 v48, v48
	v_rcp_f32_e32 v49, v49
	v_rcp_f32_e32 v42, v42
	v_rcp_f32_e32 v43, v43
	v_rcp_f32_e32 v44, v44
	v_rcp_f32_e32 v45, v45
	v_pk_mul_f32 v[38:39], v[38:39], v[46:47]
	v_pk_mul_f32 v[40:41], v[40:41], v[48:49]
	v_pk_mul_f32 v[34:35], v[34:35], v[42:43]
	v_pk_mul_f32 v[36:37], v[36:37], v[44:45]
	v_cvt_pk_bf16_f32 v46, v38, v39
	v_cvt_pk_bf16_f32 v47, v40, v41
	v_cvt_pk_bf16_f32 v48, v34, v35
	v_cvt_pk_bf16_f32 v49, v36, v37
	v_add_u32_e32 v38, 0x90, v184
	v_mad_i64_i32 v[132:133], s[8:9], v38, s20, v[130:131]
	global_store_dwordx4 v[132:133], v[46:49], off
	v_pk_mul_f32 v[22:23], v[22:23], v[30:31]
	v_pk_mul_f32 v[24:25], v[24:25], v[32:33]
	v_pk_mul_f32 v[18:19], v[18:19], v[26:27]
	v_pk_mul_f32 v[20:21], v[20:21], v[28:29]
	v_pk_mul_f32 v[30:31], v[30:31], s[6:7] op_sel_hi:[1,0]
	v_pk_mul_f32 v[32:33], v[32:33], s[6:7] op_sel_hi:[1,0]
	v_pk_mul_f32 v[26:27], v[26:27], s[6:7] op_sel_hi:[1,0]
	v_pk_mul_f32 v[28:29], v[28:29], s[6:7] op_sel_hi:[1,0]
	v_exp_f32_e32 v30, v30
	v_exp_f32_e32 v31, v31
	v_exp_f32_e32 v32, v32
	v_exp_f32_e32 v33, v33
	v_exp_f32_e32 v26, v26
	v_exp_f32_e32 v27, v27
	v_exp_f32_e32 v28, v28
	v_exp_f32_e32 v29, v29
	v_pk_add_f32 v[30:31], v[30:31], 1.0 op_sel_hi:[1,0]
	v_pk_add_f32 v[32:33], v[32:33], 1.0 op_sel_hi:[1,0]
	v_pk_add_f32 v[26:27], v[26:27], 1.0 op_sel_hi:[1,0]
	v_pk_add_f32 v[28:29], v[28:29], 1.0 op_sel_hi:[1,0]
	v_rcp_f32_e32 v30, v30
	v_rcp_f32_e32 v31, v31
	v_rcp_f32_e32 v32, v32
	v_rcp_f32_e32 v33, v33
	v_rcp_f32_e32 v26, v26
	v_rcp_f32_e32 v27, v27
	v_rcp_f32_e32 v28, v28
	v_rcp_f32_e32 v29, v29
	v_pk_mul_f32 v[22:23], v[22:23], v[30:31]
	v_pk_mul_f32 v[24:25], v[24:25], v[32:33]
	v_pk_mul_f32 v[18:19], v[18:19], v[26:27]
	v_pk_mul_f32 v[20:21], v[20:21], v[28:29]
	v_cvt_pk_bf16_f32 v30, v22, v23
	v_cvt_pk_bf16_f32 v31, v24, v25
	v_cvt_pk_bf16_f32 v32, v18, v19
	v_cvt_pk_bf16_f32 v33, v20, v21
	v_add_u32_e32 v22, 0xa0, v184
	v_mad_i64_i32 v[132:133], s[8:9], v22, s20, v[130:131]
	global_store_dwordx4 v[132:133], v[30:33], off
	v_pk_mul_f32 v[6:7], v[6:7], v[14:15]
	v_pk_mul_f32 v[8:9], v[8:9], v[16:17]
	v_pk_mul_f32 v[2:3], v[2:3], v[10:11]
	v_pk_mul_f32 v[4:5], v[4:5], v[12:13]
	v_pk_mul_f32 v[14:15], v[14:15], s[6:7] op_sel_hi:[1,0]
	v_pk_mul_f32 v[16:17], v[16:17], s[6:7] op_sel_hi:[1,0]
	v_pk_mul_f32 v[10:11], v[10:11], s[6:7] op_sel_hi:[1,0]
	v_pk_mul_f32 v[12:13], v[12:13], s[6:7] op_sel_hi:[1,0]
	v_exp_f32_e32 v14, v14
	v_exp_f32_e32 v15, v15
	v_exp_f32_e32 v16, v16
	v_exp_f32_e32 v17, v17
	v_exp_f32_e32 v10, v10
	v_exp_f32_e32 v11, v11
	v_exp_f32_e32 v12, v12
	v_exp_f32_e32 v13, v13
	v_pk_add_f32 v[14:15], v[14:15], 1.0 op_sel_hi:[1,0]
	v_pk_add_f32 v[16:17], v[16:17], 1.0 op_sel_hi:[1,0]
	v_pk_add_f32 v[10:11], v[10:11], 1.0 op_sel_hi:[1,0]
	v_pk_add_f32 v[12:13], v[12:13], 1.0 op_sel_hi:[1,0]
	v_rcp_f32_e32 v14, v14
	v_rcp_f32_e32 v15, v15
	v_rcp_f32_e32 v16, v16
	v_rcp_f32_e32 v17, v17
	v_rcp_f32_e32 v10, v10
	v_rcp_f32_e32 v11, v11
	v_rcp_f32_e32 v12, v12
	v_rcp_f32_e32 v13, v13
	v_pk_mul_f32 v[6:7], v[6:7], v[14:15]
	v_pk_mul_f32 v[8:9], v[8:9], v[16:17]
	v_pk_mul_f32 v[2:3], v[2:3], v[10:11]
	v_pk_mul_f32 v[4:5], v[4:5], v[12:13]
	v_cvt_pk_bf16_f32 v14, v6, v7
	v_cvt_pk_bf16_f32 v15, v8, v9
	v_cvt_pk_bf16_f32 v16, v2, v3
	v_cvt_pk_bf16_f32 v17, v4, v5
	v_add_u32_e32 v6, 0xb0, v184
	v_mad_i64_i32 v[132:133], s[8:9], v6, s20, v[130:131]
	global_store_dwordx4 v[132:133], v[14:17], off
	s_and_b64 vcc, exec, s[44:45]
	s_mov_b64 s[4:5], -1
	s_cbranch_vccnz .LBB0_51
	s_mov_b32 s90, 1
